# P6 norm loop: next iteration's x rows prefetched one iteration ahead (on top of v1 epilogues)
# baseline (speedup 1.0000x reference)
; __device__ __forceinline__ float bf_lo(unsigned u) { return __uint_as_float(u << 16); }
; __device__ __forceinline__ float bf_hi(unsigned u) { return __uint_as_float(u & 0xffff0000u); }
; __device__ __forceinline__ int tid_fresh() { int t = threadIdx.x; asm volatile("" : "+v"(t)); return t; }
; __device__ __forceinline__ void norm_rows_bf(const bf16_t* __restrict__ X, const float* __restrict__ g, const float* __restrict__ mod, int sh_off, int sc_off, bf16_t* __restrict__ H, int G) {
;     const int tid = tid_fresh(), lane = tid & 63, wid = tid >> 6;
;     const int gw = blockIdx.x * 8 + wid, NGW = G * 8;
;     for (int row0 = gw; row0 < MTOK; row0 += 2 * NGW) {
;         u32x4 w[2][2]; float ss[2] = {0.f, 0.f};
; #pragma unroll
;         for (int q = 0; q < 2; ++q) { const int rq = (row0 + q * NGW < MTOK) ? row0 + q * NGW : row0; const u32x4* xr = (const u32x4*)(X + (size_t)rq * DM + 16 * lane);
;             w[q][0] = xr[0]; w[q][1] = xr[1]; }
; #pragma unroll
;         for (int q = 0; q < 2; ++q) { const int row = (row0 + q * NGW < MTOK) ? row0 + q * NGW : row0; const int b = row >> 12;
;             float v[16];
; #pragma unroll
;             for (int e = 0; e < 2; ++e) { v[8 * e] = bf_lo(w[q][e].x); v[8 * e + 1] = bf_hi(w[q][e].x); v[8 * e + 2] = bf_lo(w[q][e].y); v[8 * e + 3] = bf_hi(w[q][e].y);
;                 v[8 * e + 4] = bf_lo(w[q][e].z); v[8 * e + 5] = bf_hi(w[q][e].z); v[8 * e + 6] = bf_lo(w[q][e].w); v[8 * e + 7] = bf_hi(w[q][e].w); }
; #pragma unroll
;             for (int i = 0; i < 16; ++i) ss[q] += v[i] * v[i];
;             const float rn = __builtin_amdgcn_rsqf(wave_sum(ss[q]) * (1.0f / DM) + EPS);
.LBB0_614:
	s_cmp_lt_i32 s76, 7
	s_cselect_b64 s[2:3], -1, 0
	s_and_b64 s[4:5], s[2:3], s[0:1]
	s_andn2_b64 vcc, exec, s[4:5]
	s_cbranch_vccnz .LBB0_619
	v_mov_b32_e32 v0, v175
	s_mov_b32 s2, 0x10000
	v_ashrrev_i32_e32 v1, 6, v0
	v_lshl_add_u32 v16, s92, 3, v1
	v_cmp_gt_i32_e32 vcc, s2, v16
	s_and_saveexec_b64 s[0:1], vcc
	s_cbranch_execz .LBB0_618
	v_lshlrev_b32_e32 v0, 4, v0
	v_and_b32_e32 v18, 0x3f0, v0
	v_lshlrev_b32_e32 v17, 2, v18
	global_load_dwordx4 v[0:3], v17, s[58:59] offset:48
	global_load_dwordx4 v[4:7], v17, s[58:59] offset:32
	global_load_dwordx4 v[8:11], v17, s[58:59] offset:16
	global_load_dwordx4 v[12:15], v17, s[58:59]
	v_mbcnt_lo_u32_b32 v17, -1, 0
	v_mbcnt_hi_u32_b32 v17, -1, v17
	v_and_b32_e32 v19, 64, v17
	v_add_u32_e32 v19, 64, v19
	v_xor_b32_e32 v24, 1, v17
	v_cmp_lt_i32_e32 vcc, v24, v19
	v_mov_b32_e32 v21, 0
	v_lshlrev_b32_e32 v20, 1, v18
	v_cndmask_b32_e32 v24, v17, v24, vcc
	v_lshlrev_b32_e32 v28, 2, v24
	v_xor_b32_e32 v24, 2, v17
	v_cmp_lt_i32_e32 vcc, v24, v19
	v_lshl_add_u64 v[22:23], s[66:67], 0, v[20:21]
	s_mov_b64 s[6:7], 0x36800000
	v_cndmask_b32_e32 v24, v17, v24, vcc
	v_lshlrev_b32_e32 v29, 2, v24
	v_xor_b32_e32 v24, 4, v17
	v_cmp_lt_i32_e32 vcc, v24, v19
	v_lshl_add_u64 v[22:23], v[22:23], 0, s[6:7]
	v_readlane_b32 s6, v236, 26
	v_cndmask_b32_e32 v24, v17, v24, vcc
	v_lshlrev_b32_e32 v30, 2, v24
	v_xor_b32_e32 v24, 8, v17
	v_cmp_lt_i32_e32 vcc, v24, v19
	v_readlane_b32 s7, v236, 27
	s_lshl_b32 s3, s78, 3
	v_cndmask_b32_e32 v24, v17, v24, vcc
	v_lshlrev_b32_e32 v31, 2, v24
	v_xor_b32_e32 v24, 16, v17
	v_cmp_lt_i32_e32 vcc, v24, v19
	v_mov_b32_e32 v34, 0x358637bd
	s_mov_b64 s[8:9], 0x4000
	v_cndmask_b32_e32 v24, v17, v24, vcc
	v_lshlrev_b32_e32 v32, 2, v24
	v_xor_b32_e32 v24, 32, v17
	v_cmp_lt_i32_e32 vcc, v24, v19
	s_mov_b64 s[10:11], 0x3000
	s_movk_i32 s12, 0x4000
	v_cndmask_b32_e32 v17, v17, v24, vcc
	v_lshlrev_b32_e32 v33, 2, v17
	v_lshl_add_u64 v[24:25], s[6:7], 0, v[20:21]
	s_mov_b64 s[6:7], 0
	v_lshlrev_b32_e32 v20, 2, v18
	s_movk_i32 s13, 0x3000
	s_mov_b32 s14, 0xffff
	v_mov_b32_e32 v120, v16
	v_mov_b32_e32 v121, 0
	v_add_u32_e32 v122, s3, v120
	v_mov_b32_e32 v123, 0
	v_cmp_gt_i32_e32 vcc, s2, v122
	v_lshlrev_b64 v[124:125], 11, v[120:121]
	v_lshl_add_u64 v[126:127], v[22:23], 0, v[124:125]
	v_cndmask_b32_e32 v122, v120, v122, vcc
	global_load_dwordx4 v[104:107], v[126:127], off
	global_load_dwordx4 v[108:111], v[126:127], off offset:16
	v_lshlrev_b64 v[124:125], 11, v[122:123]
	v_lshl_add_u64 v[126:127], v[22:23], 0, v[124:125]
	global_load_dwordx4 v[112:115], v[126:127], off
	global_load_dwordx4 v[116:119], v[126:127], off offset:16
.LBB0_617:
	v_ashrrev_i32_e32 v17, 31, v16
	v_lshlrev_b64 v[64:65], 11, v[16:17]
	v_lshl_add_u64 v[18:19], v[22:23], 0, v[64:65]
	v_ashrrev_i32_e32 v17, 12, v16
	v_mul_hi_i32_i24_e32 v19, 0x6000, v17
	v_mul_i32_i24_e32 v18, 0x6000, v17
	v_lshl_add_u64 v[18:19], s[66:67], 0, v[18:19]
	v_lshl_add_u64 v[66:67], v[18:19], 0, v[20:21]
	v_add_co_u32_e32 v18, vcc, s12, v66
	v_add_u32_e32 v35, s3, v16
	s_nop 0
	v_addc_co_u32_e32 v19, vcc, 0, v67, vcc
	v_cmp_gt_i32_e32 vcc, s2, v35
	global_load_dwordx4 v[44:47], v[18:19], off
	v_lshl_add_u64 v[18:19], v[66:67], 0, s[8:9]
	v_cndmask_b32_e32 v80, v16, v35, vcc
	v_ashrrev_i32_e32 v81, 31, v80
	v_lshlrev_b64 v[26:27], 11, v[80:81]
	v_lshl_add_u64 v[68:69], v[22:23], 0, v[26:27]
	global_load_dwordx4 v[48:51], v[18:19], off offset:32
	global_load_dwordx4 v[52:55], v[18:19], off offset:16
	global_load_dwordx4 v[56:59], v[18:19], off offset:48
	s_nop 0
	v_add_co_u32_e32 v86, vcc, s13, v66
	v_lshl_add_u64 v[82:83], v[24:25], 0, v[64:65]
	s_nop 0
	v_addc_co_u32_e32 v87, vcc, 0, v67, vcc
	v_lshl_add_u64 v[84:85], v[66:67], 0, s[10:11]
	global_load_dwordx4 v[64:67], v[86:87], off
	global_load_dwordx4 v[68:71], v[84:85], off offset:48
	global_load_dwordx4 v[72:75], v[84:85], off offset:32
	global_load_dwordx4 v[76:79], v[84:85], off offset:16
	v_lshl_add_u64 v[26:27], v[24:25], 0, v[26:27]
	s_waitcnt vmcnt(0)
	v_mov_b64_e32 v[36:37], v[104:105]
	v_mov_b64_e32 v[38:39], v[106:107]
	v_mov_b64_e32 v[40:41], v[108:109]
	v_mov_b64_e32 v[42:43], v[110:111]
	v_mov_b64_e32 v[60:61], v[112:113]
	v_mov_b64_e32 v[62:63], v[114:115]
	v_mov_b64_e32 v[16:17], v[116:117]
	v_mov_b64_e32 v[18:19], v[118:119]
	v_and_b32_e32 v85, 0xffff0000, v36
	v_lshlrev_b32_e32 v84, 16, v36
	v_mul_f32_e32 v81, v85, v85
	v_lshlrev_b32_e32 v36, 16, v37
	v_fmac_f32_e32 v81, v84, v84
	v_and_b32_e32 v37, 0xffff0000, v37
	v_fmac_f32_e32 v81, v36, v36
	v_lshlrev_b32_e32 v86, 16, v38
	v_fmac_f32_e32 v81, v37, v37
	v_and_b32_e32 v87, 0xffff0000, v38
	v_fmac_f32_e32 v81, v86, v86
	v_lshlrev_b32_e32 v38, 16, v39
	v_fmac_f32_e32 v81, v87, v87
	v_and_b32_e32 v39, 0xffff0000, v39
	v_fmac_f32_e32 v81, v38, v38
	v_lshlrev_b32_e32 v88, 16, v40
	v_fmac_f32_e32 v81, v39, v39
	v_and_b32_e32 v89, 0xffff0000, v40
	v_fmac_f32_e32 v81, v88, v88
	v_lshlrev_b32_e32 v40, 16, v41
	v_fmac_f32_e32 v81, v89, v89
	v_and_b32_e32 v41, 0xffff0000, v41
	v_fmac_f32_e32 v81, v40, v40
	v_lshlrev_b32_e32 v90, 16, v42
	v_fmac_f32_e32 v81, v41, v41
	v_and_b32_e32 v91, 0xffff0000, v42
	v_and_b32_e32 v42, 0xffff0000, v43
	v_lshlrev_b32_e32 v43, 16, v43
	v_fmac_f32_e32 v81, v90, v90
	v_pk_mul_f32 v[92:93], v[42:43], v[42:43]
	v_fmac_f32_e32 v81, v91, v91
	v_add_f32_e32 v81, v93, v81
	v_add_f32_e32 v81, v92, v81
	ds_bpermute_b32 v92, v28, v81
	v_lshlrev_b32_e32 v94, 16, v61
	v_and_b32_e32 v95, 0xffff0000, v61
	v_lshlrev_b32_e32 v102, 16, v18
	v_and_b32_e32 v103, 0xffff0000, v18
	s_waitcnt lgkmcnt(0)
	v_add_f32_e32 v81, v81, v92
	ds_bpermute_b32 v93, v29, v81
	v_lshlrev_b32_e32 v92, 16, v60
	v_lshlrev_b32_e32 v96, 16, v62
	v_lshlrev_b32_e32 v98, 16, v63
	v_and_b32_e32 v99, 0xffff0000, v63
	s_waitcnt lgkmcnt(0)
; __device__ __forceinline__ unsigned pk2(float lo, float hi) { f32x2 v = {lo, hi}; bf16x2_t b = __builtin_convertvector(v, bf16x2_t); return __builtin_bit_cast(unsigned, b); }
; __device__ __forceinline__ float bf_lo(unsigned u) { return __uint_as_float(u << 16); }
; __device__ __forceinline__ float bf_hi(unsigned u) { return __uint_as_float(u & 0xffff0000u); }
; __device__ __forceinline__ void norm_rows_bf(const bf16_t* __restrict__ X, const float* __restrict__ g, const float* __restrict__ mod, int sh_off, int sc_off, bf16_t* __restrict__ H, int G) {
;     ...
;         for (int q = 0; q < 2; ++q) { const int row = (row0 + q * NGW < MTOK) ? row0 + q * NGW : row0; const int b = row >> 12;
;             float v[16];
; #pragma unroll
;             for (int e = 0; e < 2; ++e) { v[8 * e] = bf_lo(w[q][e].x); v[8 * e + 1] = bf_hi(w[q][e].x); v[8 * e + 2] = bf_lo(w[q][e].y); v[8 * e + 3] = bf_hi(w[q][e].y);
;                 v[8 * e + 4] = bf_lo(w[q][e].z); v[8 * e + 5] = bf_hi(w[q][e].z); v[8 * e + 6] = bf_lo(w[q][e].w); v[8 * e + 7] = bf_hi(w[q][e].w); }
; #pragma unroll
;             for (int i = 0; i < 16; ++i) ss[q] += v[i] * v[i];
;             const float rn = __builtin_amdgcn_rsqf(wave_sum(ss[q]) * (1.0f / DM) + EPS);
;             const float* mb = mod + (size_t)b * NMOD; const int c = 16 * lane;
;             unsigned o[8];
; #pragma unroll
;             for (int j = 0; j < 4; ++j) { const f32x4 gv = *(const f32x4*)(g + c + 4 * j), sc = *(const f32x4*)(mb + sc_off + c + 4 * j), sh = *(const f32x4*)(mb + sh_off + c + 4 * j);
;                 const f32x4 x = (f32x4){v[4 * j], v[4 * j + 1], v[4 * j + 2], v[4 * j + 3]};
;                 const f32x4 y = x * rn * gv * (sc + 1.0f) + sh; o[2 * j] = pk2(y[0], y[1]); o[2 * j + 1] = pk2(y[2], y[3]); }
;             u32x4* op = (u32x4*)(H + (size_t)row * DM + c);
;             op[0] = (u32x4){o[0], o[1], o[2], o[3]}; op[1] = (u32x4){o[4], o[5], o[6], o[7]}; }
	v_add_f32_e32 v81, v81, v93
	ds_bpermute_b32 v97, v30, v81
	v_and_b32_e32 v93, 0xffff0000, v60
	v_pk_add_f32 v[46:47], v[46:47], 1.0 op_sel_hi:[1,0]
	v_pk_add_f32 v[44:45], v[44:45], 1.0 op_sel_hi:[1,0]
	v_pk_add_f32 v[54:55], v[54:55], 1.0 op_sel_hi:[1,0]
	s_waitcnt lgkmcnt(0)
	v_add_f32_e32 v60, v81, v97
	ds_bpermute_b32 v61, v31, v60
	v_and_b32_e32 v97, 0xffff0000, v62
	v_pk_add_f32 v[52:53], v[52:53], 1.0 op_sel_hi:[1,0]
	v_pk_add_f32 v[50:51], v[50:51], 1.0 op_sel_hi:[1,0]
	v_pk_add_f32 v[48:49], v[48:49], 1.0 op_sel_hi:[1,0]
	s_waitcnt lgkmcnt(0)
	v_add_f32_e32 v60, v60, v61
	ds_bpermute_b32 v61, v32, v60
	v_pk_add_f32 v[58:59], v[58:59], 1.0 op_sel_hi:[1,0]
	v_pk_add_f32 v[56:57], v[56:57], 1.0 op_sel_hi:[1,0]
	v_mul_f32_e32 v81, v93, v93
	v_fmac_f32_e32 v81, v92, v92
	s_waitcnt lgkmcnt(0)
	v_add_f32_e32 v60, v60, v61
	ds_bpermute_b32 v61, v33, v60
	v_fmac_f32_e32 v81, v94, v94
	v_fmac_f32_e32 v81, v95, v95
	v_fmac_f32_e32 v81, v96, v96
	v_fmac_f32_e32 v81, v97, v97
	s_waitcnt lgkmcnt(0)
	v_add_f32_e32 v18, v60, v61
	v_fmamk_f32 v18, v18, 0x3a800000, v34
	v_rsq_f32_e32 v18, v18
	v_fmac_f32_e32 v81, v98, v98
	v_lshlrev_b32_e32 v100, 16, v16
	v_fmac_f32_e32 v81, v99, v99
	v_pk_mul_f32 v[36:37], v[36:37], v[18:19] op_sel_hi:[1,0]
	v_pk_mul_f32 v[60:61], v[84:85], v[18:19] op_sel_hi:[1,0]
	v_pk_mul_f32 v[38:39], v[38:39], v[18:19] op_sel_hi:[1,0]
	v_pk_mul_f32 v[62:63], v[86:87], v[18:19] op_sel_hi:[1,0]
	v_pk_mul_f32 v[40:41], v[40:41], v[18:19] op_sel_hi:[1,0]
	v_pk_mul_f32 v[84:85], v[88:89], v[18:19] op_sel_hi:[1,0]
	v_pk_mul_f32 v[42:43], v[42:43], v[18:19] op_sel:[1,0] op_sel_hi:[0,0]
	v_pk_mul_f32 v[86:87], v[90:91], v[18:19] op_sel_hi:[1,0]
	v_pk_mul_f32 v[60:61], v[12:13], v[60:61]
	v_pk_mul_f32 v[36:37], v[14:15], v[36:37]
	v_pk_mul_f32 v[62:63], v[8:9], v[62:63]
	v_pk_mul_f32 v[38:39], v[10:11], v[38:39]
	v_pk_mul_f32 v[84:85], v[4:5], v[84:85]
	v_pk_mul_f32 v[40:41], v[6:7], v[40:41]
	v_pk_mul_f32 v[86:87], v[0:1], v[86:87]
	v_pk_mul_f32 v[42:43], v[2:3], v[42:43]
	v_pk_fma_f32 v[46:47], v[46:47], v[36:37], v[66:67]
	v_pk_fma_f32 v[36:37], v[44:45], v[60:61], v[64:65]
	v_pk_fma_f32 v[44:45], v[54:55], v[38:39], v[78:79]
	v_pk_fma_f32 v[38:39], v[52:53], v[62:63], v[76:77]
	v_pk_fma_f32 v[50:51], v[50:51], v[40:41], v[74:75]
	v_pk_fma_f32 v[40:41], v[48:49], v[84:85], v[72:73]
	v_pk_fma_f32 v[48:49], v[58:59], v[42:43], v[70:71]
	v_pk_fma_f32 v[42:43], v[56:57], v[86:87], v[68:69]
	v_cvt_pk_bf16_f32 v36, v36, v37
	v_cvt_pk_bf16_f32 v37, v46, v47
	v_cvt_pk_bf16_f32 v38, v38, v39
	v_cvt_pk_bf16_f32 v39, v44, v45
	v_ashrrev_i32_e32 v18, 12, v80
	v_cvt_pk_bf16_f32 v40, v40, v41
	v_cvt_pk_bf16_f32 v41, v50, v51
	v_cvt_pk_bf16_f32 v42, v42, v43
	v_cvt_pk_bf16_f32 v43, v48, v49
	global_store_dwordx4 v[82:83], v[36:39], off
	global_store_dwordx4 v[82:83], v[40:43], off offset:16
	v_and_b32_e32 v101, 0xffff0000, v16
	v_mul_hi_i32_i24_e32 v37, 0x6000, v18
	v_mul_i32_i24_e32 v36, 0x6000, v18
	v_lshl_add_u64 v[36:37], s[66:67], 0, v[36:37]
	v_lshl_add_u64 v[48:49], v[36:37], 0, v[20:21]
	v_add_co_u32_e32 v50, vcc, s12, v48
	v_lshl_add_u64 v[68:69], v[48:49], 0, s[8:9]
	s_nop 0
	v_addc_co_u32_e32 v51, vcc, 0, v49, vcc
	global_load_dwordx4 v[36:39], v[50:51], off
	global_load_dwordx4 v[40:43], v[68:69], off offset:32
	global_load_dwordx4 v[44:47], v[68:69], off offset:16
	v_add_co_u32_e32 v72, vcc, s13, v48
	v_lshl_add_u64 v[70:71], v[48:49], 0, s[10:11]
	s_nop 0
	v_addc_co_u32_e32 v73, vcc, 0, v49, vcc
	global_load_dwordx4 v[48:51], v[72:73], off
	global_load_dwordx4 v[52:55], v[68:69], off offset:48
	global_load_dwordx4 v[56:59], v[70:71], off offset:16
	global_load_dwordx4 v[60:63], v[70:71], off offset:48
	global_load_dwordx4 v[64:67], v[70:71], off offset:32
	v_add_u32_e32 v120, s3, v35
	v_min_i32_e32 v120, s14, v120
	v_mov_b32_e32 v121, 0
	v_add_u32_e32 v122, s3, v120
	v_mov_b32_e32 v123, 0
	v_cmp_gt_i32_e32 vcc, s2, v122
	v_lshlrev_b64 v[124:125], 11, v[120:121]
	v_lshl_add_u64 v[126:127], v[22:23], 0, v[124:125]
	v_cndmask_b32_e32 v122, v120, v122, vcc
	global_load_dwordx4 v[104:107], v[126:127], off
	global_load_dwordx4 v[108:111], v[126:127], off offset:16
	v_lshlrev_b64 v[124:125], 11, v[122:123]
	v_lshl_add_u64 v[126:127], v[22:23], 0, v[124:125]
	global_load_dwordx4 v[112:115], v[126:127], off
	global_load_dwordx4 v[116:119], v[126:127], off offset:16
	v_fmac_f32_e32 v81, v100, v100
	v_lshlrev_b32_e32 v16, 16, v17
	v_fmac_f32_e32 v81, v101, v101
	v_and_b32_e32 v17, 0xffff0000, v17
	v_fmac_f32_e32 v81, v16, v16
	v_fmac_f32_e32 v81, v17, v17
	v_fmac_f32_e32 v81, v102, v102
	v_and_b32_e32 v18, 0xffff0000, v19
	v_lshlrev_b32_e32 v19, 16, v19
	v_fmac_f32_e32 v81, v103, v103
	v_pk_mul_f32 v[68:69], v[18:19], v[18:19]
	s_waitcnt vmcnt(11)
; __device__ __forceinline__ unsigned pk2(float lo, float hi) { f32x2 v = {lo, hi}; bf16x2_t b = __builtin_convertvector(v, bf16x2_t); return __builtin_bit_cast(unsigned, b); }
; __device__ __forceinline__ void norm_rows_bf(const bf16_t* __restrict__ X, const float* __restrict__ g, const float* __restrict__ mod, int sh_off, int sc_off, bf16_t* __restrict__ H, int G) {
;     ...
;             for (int i = 0; i < 16; ++i) ss[q] += v[i] * v[i];
;             const float rn = __builtin_amdgcn_rsqf(wave_sum(ss[q]) * (1.0f / DM) + EPS);
;             const float* mb = mod + (size_t)b * NMOD; const int c = 16 * lane;
;             unsigned o[8];
; #pragma unroll
;             for (int j = 0; j < 4; ++j) { const f32x4 gv = *(const f32x4*)(g + c + 4 * j), sc = *(const f32x4*)(mb + sc_off + c + 4 * j), sh = *(const f32x4*)(mb + sh_off + c + 4 * j);
;                 const f32x4 x = (f32x4){v[4 * j], v[4 * j + 1], v[4 * j + 2], v[4 * j + 3]};
;                 const f32x4 y = x * rn * gv * (sc + 1.0f) + sh; o[2 * j] = pk2(y[0], y[1]); o[2 * j + 1] = pk2(y[2], y[3]); }
;             u32x4* op = (u32x4*)(H + (size_t)row * DM + c);
;             op[0] = (u32x4){o[0], o[1], o[2], o[3]}; op[1] = (u32x4){o[4], o[5], o[6], o[7]}; }
;     }
	v_pk_add_f32 v[36:37], v[36:37], 1.0 op_sel_hi:[1,0]
	v_add_f32_e32 v69, v69, v81
	v_add_f32_e32 v68, v68, v69
	ds_bpermute_b32 v69, v28, v68
	s_waitcnt vmcnt(9)
	v_pk_add_f32 v[44:45], v[44:45], 1.0 op_sel_hi:[1,0]
	v_pk_add_f32 v[42:43], v[42:43], 1.0 op_sel_hi:[1,0]
	v_pk_add_f32 v[40:41], v[40:41], 1.0 op_sel_hi:[1,0]
	s_waitcnt lgkmcnt(0)
	v_add_f32_e32 v68, v68, v69
	ds_bpermute_b32 v69, v29, v68
	s_waitcnt lgkmcnt(0)
	v_add_f32_e32 v68, v68, v69
	ds_bpermute_b32 v69, v30, v68
	s_waitcnt lgkmcnt(0)
	v_add_f32_e32 v68, v68, v69
	ds_bpermute_b32 v69, v31, v68
	s_waitcnt lgkmcnt(0)
	v_add_f32_e32 v68, v68, v69
	ds_bpermute_b32 v69, v32, v68
	s_waitcnt lgkmcnt(0)
	v_add_f32_e32 v68, v68, v69
	ds_bpermute_b32 v69, v33, v68
	s_waitcnt lgkmcnt(0)
	v_add_f32_e32 v68, v68, v69
	v_fmamk_f32 v68, v68, 0x3a800000, v34
	v_rsq_f32_e32 v68, v68
	s_nop 0
	v_pk_mul_f32 v[70:71], v[94:95], v[68:69] op_sel_hi:[1,0]
	v_pk_mul_f32 v[72:73], v[92:93], v[68:69] op_sel_hi:[1,0]
	v_pk_mul_f32 v[74:75], v[98:99], v[68:69] op_sel_hi:[1,0]
	v_pk_mul_f32 v[76:77], v[96:97], v[68:69] op_sel_hi:[1,0]
	v_pk_mul_f32 v[78:79], v[100:101], v[68:69] op_sel_hi:[1,0]
	v_pk_mul_f32 v[80:81], v[18:19], v[68:69] op_sel:[1,0] op_sel_hi:[0,0]
	v_pk_mul_f32 v[18:19], v[102:103], v[68:69] op_sel_hi:[1,0]
	v_pk_mul_f32 v[16:17], v[16:17], v[68:69] op_sel_hi:[1,0]
	v_pk_mul_f32 v[68:69], v[12:13], v[72:73]
	v_pk_mul_f32 v[70:71], v[14:15], v[70:71]
	v_pk_mul_f32 v[72:73], v[8:9], v[76:77]
	v_pk_mul_f32 v[74:75], v[10:11], v[74:75]
	v_pk_mul_f32 v[76:77], v[4:5], v[78:79]
	v_pk_mul_f32 v[78:79], v[0:1], v[18:19]
	v_pk_add_f32 v[18:19], v[38:39], 1.0 op_sel_hi:[1,0]
	v_pk_add_f32 v[38:39], v[46:47], 1.0 op_sel_hi:[1,0]
	v_pk_mul_f32 v[16:17], v[6:7], v[16:17]
	s_waitcnt vmcnt(8)
	v_pk_fma_f32 v[18:19], v[18:19], v[70:71], v[50:51]
	v_pk_fma_f32 v[36:37], v[36:37], v[68:69], v[48:49]
	s_waitcnt vmcnt(6)
	v_pk_fma_f32 v[38:39], v[38:39], v[74:75], v[58:59]
	v_pk_fma_f32 v[44:45], v[44:45], v[72:73], v[56:57]
	s_waitcnt vmcnt(4)
	v_pk_fma_f32 v[42:43], v[42:43], v[16:17], v[66:67]
	v_pk_fma_f32 v[40:41], v[40:41], v[76:77], v[64:65]
	v_cvt_pk_bf16_f32 v16, v36, v37
	v_cvt_pk_bf16_f32 v17, v18, v19
	v_cvt_pk_bf16_f32 v18, v44, v45
	v_cvt_pk_bf16_f32 v19, v38, v39
	v_cvt_pk_bf16_f32 v36, v40, v41
	v_cvt_pk_bf16_f32 v37, v42, v43
	v_pk_mul_f32 v[38:39], v[2:3], v[80:81]
	v_pk_add_f32 v[40:41], v[54:55], 1.0 op_sel_hi:[1,0]
	v_pk_add_f32 v[42:43], v[52:53], 1.0 op_sel_hi:[1,0]
	global_store_dwordx4 v[26:27], v[16:19], off
	v_pk_fma_f32 v[40:41], v[40:41], v[38:39], v[62:63]
	v_pk_fma_f32 v[38:39], v[42:43], v[78:79], v[60:61]
	v_add_u32_e32 v16, s3, v35
	v_cmp_lt_i32_e32 vcc, s14, v16
	v_cvt_pk_bf16_f32 v38, v38, v39
	v_cvt_pk_bf16_f32 v39, v40, v41
	s_or_b64 s[6:7], vcc, s[6:7]
	global_store_dwordx4 v[26:27], v[36:39], off offset:16
	s_andn2_b64 exec, exec, s[6:7]
	s_cbranch_execnz .LBB0_617
